# K-loop head segment: LDS wait placed directly before its barrier, after the scalar pointer selects
# speedup vs baseline: 1.0075x; 1.0057x over previous
; #define PG8_STAGE(bufoff, gbase, voff) do { _Pragma("unroll") for (int _i = 0; _i < 2; ++_i) \
;         __builtin_amdgcn_global_load_lds((const unsigned*)((const char*)(gbase) + (voff)[_i]), (PG8_LAS unsigned*)(lds + (bufoff) + ldsw + _i * 8192), 16, 0, 0); } while (0)
; #define PG8_LDA(dst, b, h) do { _Pragma("unroll") for (int m = 0; m < 4; ++m) _Pragma("unroll") for (int k = 0; k < 2; ++k) dst[m][k] = *(const PG8_LAS bf16x8*)(lds + PG8_SA(b, h) + aoff + m * 2048 + k * 1024); } while (0)
; #define PG8_MMA(ai, bj, At, Bt) do { __builtin_amdgcn_s_setprio(1); _Pragma("unroll") for (int m = 0; m < 4; ++m) _Pragma("unroll") for (int n = 0; n < 2; ++n) _Pragma("unroll") for (int k = 0; k < 2; ++k) \
;         acc[ai][bj][m][n] = __builtin_amdgcn_mfma_f32_16x16x32_bf16(Bt[n][k], At[m][k], acc[ai][bj][m][n], 0, 0, 0); __builtin_amdgcn_s_setprio(0); } while (0)
; #define PG8_WAIT_V(n) asm volatile("s_waitcnt vmcnt(" #n ")" ::: "memory")
; #define PG8_WAIT_VN(n) asm volatile("s_waitcnt vmcnt(%0)" :: "n"(n) : "memory")
; #define PG8_WAIT_L(n) asm volatile("s_waitcnt lgkmcnt(" #n ")" ::: "memory")
; #define PG8_BAR __builtin_amdgcn_s_barrier()
; #define PG8_SCHED __builtin_amdgcn_sched_barrier(0)
; template <class Epi, class Sched, bool ALIGN_EPI = false, bool SP2 = false>
; __device__ __forceinline__ void gemm_phase(PG8_LAS unsigned char* lds, const Gemm g, const Sched& S, const Epi& E, const int wave_id) {
;     ...
;             const char* a1 = cA + (size_t)(t + 1) * kstep;
;             const char* a2 = last ? nA : cA + (size_t)(t + 2) * kstep; const char* b2 = last ? nB : cB + (size_t)(t + 2) * kstep;
;     ...
;             PG8_WAIT_VN(8 + Epi::NS); if (strict) PG8_WAIT_V(8); PG8_WAIT_L(0); PG8_BAR; PG8_MMA(0, 0, At, B0); PG8_MMA(0, 1, At, B1); PG8_BAR; PG8_SCHED;
;             PG8_LDA(At, 0, 1); PG8_STAGE(PG8_SB(0, 0), b2, voffB); PG8_STAGE(PG8_SB(0, 1), b2 + hstep, voffB); PG8_STAGE(PG8_SA(0, 0), a2, voffA);
;             PG8_WAIT_VN(8 + Epi::NS); if (strict) PG8_WAIT_V(8); PG8_WAIT_L(0); PG8_BAR; PG8_MMA(1, 0, At, B0); PG8_MMA(1, 1, At, B1); PG8_BAR; PG8_SCHED;
.LBB0_160:
	s_add_u32 s24, s20, s22
	s_addc_u32 s25, s21, s23
	s_add_u32 s24, s24, 0x100
	s_addc_u32 s25, s25, 0
	s_add_u32 s53, s74, s22
	s_addc_u32 s78, s75, s23
	s_cmpk_eq_i32 s22, 0x700
	s_cselect_b32 s27, s13, s25
	s_cselect_b32 s26, s68, s24
	s_cselect_b32 s25, s11, s78
	s_cselect_b32 s24, s69, s53
	s_waitcnt lgkmcnt(0)
	s_barrier
	s_setprio 1
	s_waitcnt lgkmcnt(0)
	v_mfma_f32_16x16x32_bf16 v[126:129], v[146:149], v[186:189], v[126:129]
	v_mfma_f32_16x16x32_bf16 v[122:125], v[154:157], v[186:189], v[122:125]
	v_mfma_f32_16x16x32_bf16 v[118:121], v[146:149], v[178:181], v[118:121]
	v_mfma_f32_16x16x32_bf16 v[114:117], v[154:157], v[178:181], v[114:117]
	v_mfma_f32_16x16x32_bf16 v[94:97], v[146:149], v[170:173], v[94:97]
	v_mfma_f32_16x16x32_bf16 v[90:93], v[154:157], v[170:173], v[90:93]
	v_mfma_f32_16x16x32_bf16 v[86:89], v[146:149], v[162:165], v[86:89]
	v_mfma_f32_16x16x32_bf16 v[82:85], v[154:157], v[162:165], v[82:85]
	v_mfma_f32_16x16x32_bf16 v[126:129], v[150:153], v[190:193], v[126:129]
	v_mfma_f32_16x16x32_bf16 v[122:125], v[158:161], v[190:193], v[122:125]
	v_mfma_f32_16x16x32_bf16 v[118:121], v[150:153], v[182:185], v[118:121]
	v_mfma_f32_16x16x32_bf16 v[114:117], v[158:161], v[182:185], v[114:117]
	v_mfma_f32_16x16x32_bf16 v[94:97], v[150:153], v[174:177], v[94:97]
	v_mfma_f32_16x16x32_bf16 v[90:93], v[158:161], v[174:177], v[90:93]
	v_mfma_f32_16x16x32_bf16 v[86:89], v[150:153], v[166:169], v[86:89]
	v_mfma_f32_16x16x32_bf16 v[82:85], v[158:161], v[166:169], v[82:85]
	s_setprio 0
	s_setprio 1
	v_mfma_f32_16x16x32_bf16 v[110:113], v[130:133], v[186:189], v[110:113]
	v_mfma_f32_16x16x32_bf16 v[106:109], v[138:141], v[186:189], v[106:109]
	v_mfma_f32_16x16x32_bf16 v[102:105], v[130:133], v[178:181], v[102:105]
	v_mfma_f32_16x16x32_bf16 v[98:101], v[138:141], v[178:181], v[98:101]
	v_mfma_f32_16x16x32_bf16 v[78:81], v[130:133], v[170:173], v[78:81]
	v_mfma_f32_16x16x32_bf16 v[74:77], v[138:141], v[170:173], v[74:77]
	v_mfma_f32_16x16x32_bf16 v[70:73], v[130:133], v[162:165], v[70:73]
	v_mfma_f32_16x16x32_bf16 v[66:69], v[138:141], v[162:165], v[66:69]
	v_mfma_f32_16x16x32_bf16 v[110:113], v[134:137], v[190:193], v[110:113]
	v_mfma_f32_16x16x32_bf16 v[106:109], v[142:145], v[190:193], v[106:109]
	v_mfma_f32_16x16x32_bf16 v[102:105], v[134:137], v[182:185], v[102:105]
	v_mfma_f32_16x16x32_bf16 v[98:101], v[142:145], v[182:185], v[98:101]
	v_mfma_f32_16x16x32_bf16 v[78:81], v[134:137], v[174:177], v[78:81]
	v_mfma_f32_16x16x32_bf16 v[74:77], v[142:145], v[174:177], v[74:77]
	v_mfma_f32_16x16x32_bf16 v[70:73], v[134:137], v[166:169], v[70:73]
	v_mfma_f32_16x16x32_bf16 v[66:69], v[142:145], v[166:169], v[66:69]
	s_setprio 0
	s_barrier
	s_mov_b32 m0, s42
	v_lshl_add_u64 v[232:233], s[24:25], 0, v[212:213]
	s_add_u32 s90, s24, 0x40000
	ds_read_b128 v[186:189], v249 offset:16384
	ds_read_b128 v[190:193], v249 offset:17408
	ds_read_b128 v[178:181], v249 offset:18432
	ds_read_b128 v[182:185], v249 offset:19456
	ds_read_b128 v[170:173], v249 offset:20480
	ds_read_b128 v[174:177], v249 offset:21504
	ds_read_b128 v[162:165], v249 offset:22528
	ds_read_b128 v[166:169], v249 offset:23552
	global_load_lds_dwordx4 v[232:233], off
	v_lshl_add_u64 v[230:231], s[24:25], 0, v[216:217]
	s_mov_b32 m0, s43
	s_addc_u32 s91, s25, 0
	global_load_lds_dwordx4 v[230:231], off
	v_lshl_add_u64 v[194:195], s[90:91], 0, v[212:213]
	s_mov_b32 m0, s49
	v_lshl_add_u64 v[226:227], s[26:27], 0, v[210:211]
	global_load_lds_dwordx4 v[194:195], off
	v_lshl_add_u64 v[194:195], s[90:91], 0, v[216:217]
	s_mov_b32 m0, s50
	v_lshl_add_u64 v[228:229], s[26:27], 0, v[214:215]
	global_load_lds_dwordx4 v[194:195], off
	s_mov_b32 m0, s41
	s_andn2_b64 vcc, exec, s[28:29]
	global_load_lds_dwordx4 v[226:227], off
	s_mov_b32 m0, s51
	s_nop 0
	global_load_lds_dwordx4 v[228:229], off
	s_waitcnt vmcnt(16)
	s_cbranch_vccnz .LBB0_157
	s_waitcnt vmcnt(8)
	s_branch .LBB0_157

; #define PG8_STAGE(bufoff, gbase, voff) do { _Pragma("unroll") for (int _i = 0; _i < 2; ++_i) \
;         __builtin_amdgcn_global_load_lds((const unsigned*)((const char*)(gbase) + (voff)[_i]), (PG8_LAS unsigned*)(lds + (bufoff) + ldsw + _i * 8192), 16, 0, 0); } while (0)
; #define PG8_LDA(dst, b, h) do { _Pragma("unroll") for (int m = 0; m < 4; ++m) _Pragma("unroll") for (int k = 0; k < 2; ++k) dst[m][k] = *(const PG8_LAS bf16x8*)(lds + PG8_SA(b, h) + aoff + m * 2048 + k * 1024); } while (0)
; #define PG8_MMA(ai, bj, At, Bt) do { __builtin_amdgcn_s_setprio(1); _Pragma("unroll") for (int m = 0; m < 4; ++m) _Pragma("unroll") for (int n = 0; n < 2; ++n) _Pragma("unroll") for (int k = 0; k < 2; ++k) \
;         acc[ai][bj][m][n] = __builtin_amdgcn_mfma_f32_16x16x32_bf16(Bt[n][k], At[m][k], acc[ai][bj][m][n], 0, 0, 0); __builtin_amdgcn_s_setprio(0); } while (0)
; #define PG8_WAIT_V(n) asm volatile("s_waitcnt vmcnt(" #n ")" ::: "memory")
; #define PG8_WAIT_VN(n) asm volatile("s_waitcnt vmcnt(%0)" :: "n"(n) : "memory")
; #define PG8_WAIT_L(n) asm volatile("s_waitcnt lgkmcnt(" #n ")" ::: "memory")
; #define PG8_BAR __builtin_amdgcn_s_barrier()
; #define PG8_SCHED __builtin_amdgcn_sched_barrier(0)
; template <class Epi, class Sched, bool ALIGN_EPI = false, bool SP2 = false>
; __device__ __forceinline__ void gemm_phase(PG8_LAS unsigned char* lds, const Gemm g, const Sched& S, const Epi& E, const int wave_id) {
;     ...
;             const char* a1 = cA + (size_t)(t + 1) * kstep;
;             const char* a2 = last ? nA : cA + (size_t)(t + 2) * kstep; const char* b2 = last ? nB : cB + (size_t)(t + 2) * kstep;
;     ...
;             PG8_WAIT_VN(8 + Epi::NS); if (strict) PG8_WAIT_V(8); PG8_WAIT_L(0); PG8_BAR; PG8_MMA(0, 0, At, B0); PG8_MMA(0, 1, At, B1); PG8_BAR; PG8_SCHED;
;             PG8_LDA(At, 0, 1); PG8_STAGE(PG8_SB(0, 0), b2, voffB); PG8_STAGE(PG8_SB(0, 1), b2 + hstep, voffB); PG8_STAGE(PG8_SA(0, 0), a2, voffA);
;             PG8_WAIT_VN(8 + Epi::NS); if (strict) PG8_WAIT_V(8); PG8_WAIT_L(0); PG8_BAR; PG8_MMA(1, 0, At, B0); PG8_MMA(1, 1, At, B1); PG8_BAR; PG8_SCHED;
.LBB0_238:
	s_add_u32 s16, s12, s14
	s_addc_u32 s17, s13, s15
	s_add_u32 s16, s16, 0x100
	s_addc_u32 s17, s17, 0
	s_add_u32 s53, s57, s14
	s_addc_u32 s67, s62, s15
	s_cmpk_eq_i32 s14, 0x1500
	s_cselect_b32 s19, s7, s17
	s_cselect_b32 s18, s6, s16
	s_cselect_b32 s17, s11, s67
	s_cselect_b32 s16, s10, s53
	s_waitcnt lgkmcnt(0)
	s_barrier
	s_setprio 1
	s_waitcnt lgkmcnt(0)
	v_mfma_f32_16x16x32_bf16 v[126:129], v[146:149], v[186:189], v[126:129]
	v_mfma_f32_16x16x32_bf16 v[122:125], v[154:157], v[186:189], v[122:125]
	v_mfma_f32_16x16x32_bf16 v[110:113], v[146:149], v[178:181], v[110:113]
	v_mfma_f32_16x16x32_bf16 v[106:109], v[154:157], v[178:181], v[106:109]
	v_mfma_f32_16x16x32_bf16 v[94:97], v[146:149], v[170:173], v[94:97]
	v_mfma_f32_16x16x32_bf16 v[90:93], v[154:157], v[170:173], v[90:93]
	v_mfma_f32_16x16x32_bf16 v[78:81], v[146:149], v[162:165], v[78:81]
	v_mfma_f32_16x16x32_bf16 v[74:77], v[154:157], v[162:165], v[74:77]
	v_mfma_f32_16x16x32_bf16 v[126:129], v[150:153], v[190:193], v[126:129]
	v_mfma_f32_16x16x32_bf16 v[122:125], v[158:161], v[190:193], v[122:125]
	v_mfma_f32_16x16x32_bf16 v[110:113], v[150:153], v[182:185], v[110:113]
	v_mfma_f32_16x16x32_bf16 v[106:109], v[158:161], v[182:185], v[106:109]
	v_mfma_f32_16x16x32_bf16 v[94:97], v[150:153], v[174:177], v[94:97]
	v_mfma_f32_16x16x32_bf16 v[90:93], v[158:161], v[174:177], v[90:93]
	v_mfma_f32_16x16x32_bf16 v[78:81], v[150:153], v[166:169], v[78:81]
	v_mfma_f32_16x16x32_bf16 v[74:77], v[158:161], v[166:169], v[74:77]
	s_setprio 0
	s_setprio 1
	v_mfma_f32_16x16x32_bf16 v[118:121], v[130:133], v[186:189], v[118:121]
	v_mfma_f32_16x16x32_bf16 v[114:117], v[138:141], v[186:189], v[114:117]
	v_mfma_f32_16x16x32_bf16 v[102:105], v[130:133], v[178:181], v[102:105]
	v_mfma_f32_16x16x32_bf16 v[98:101], v[138:141], v[178:181], v[98:101]
	v_mfma_f32_16x16x32_bf16 v[86:89], v[130:133], v[170:173], v[86:89]
	v_mfma_f32_16x16x32_bf16 v[82:85], v[138:141], v[170:173], v[82:85]
	v_mfma_f32_16x16x32_bf16 v[70:73], v[130:133], v[162:165], v[70:73]
	v_mfma_f32_16x16x32_bf16 v[66:69], v[138:141], v[162:165], v[66:69]
	v_mfma_f32_16x16x32_bf16 v[118:121], v[134:137], v[190:193], v[118:121]
	v_mfma_f32_16x16x32_bf16 v[114:117], v[142:145], v[190:193], v[114:117]
	v_mfma_f32_16x16x32_bf16 v[102:105], v[134:137], v[182:185], v[102:105]
	v_mfma_f32_16x16x32_bf16 v[98:101], v[142:145], v[182:185], v[98:101]
	v_mfma_f32_16x16x32_bf16 v[86:89], v[134:137], v[174:177], v[86:89]
	v_mfma_f32_16x16x32_bf16 v[82:85], v[142:145], v[174:177], v[82:85]
	v_mfma_f32_16x16x32_bf16 v[70:73], v[134:137], v[166:169], v[70:73]
	v_mfma_f32_16x16x32_bf16 v[66:69], v[142:145], v[166:169], v[66:69]
	s_setprio 0
	s_barrier
	s_mov_b32 m0, s34
	v_lshl_add_u64 v[232:233], s[16:17], 0, v[212:213]
	s_add_u32 s68, s16, 0xb0000
	ds_read_b128 v[186:189], v247 offset:16384
	ds_read_b128 v[190:193], v247 offset:17408
	ds_read_b128 v[178:181], v247 offset:18432
	ds_read_b128 v[182:185], v247 offset:19456
	ds_read_b128 v[170:173], v247 offset:20480
	ds_read_b128 v[174:177], v247 offset:21504
	ds_read_b128 v[162:165], v247 offset:22528
	ds_read_b128 v[166:169], v247 offset:23552
	global_load_lds_dwordx4 v[232:233], off
	v_lshl_add_u64 v[230:231], s[16:17], 0, v[216:217]
	s_mov_b32 m0, s35
	s_addc_u32 s69, s17, 0
	global_load_lds_dwordx4 v[230:231], off
	v_lshl_add_u64 v[194:195], s[68:69], 0, v[212:213]
	s_mov_b32 m0, s36
	v_lshl_add_u64 v[226:227], s[18:19], 0, v[210:211]
	global_load_lds_dwordx4 v[194:195], off
	v_lshl_add_u64 v[194:195], s[68:69], 0, v[216:217]
	s_mov_b32 m0, s37
	v_lshl_add_u64 v[228:229], s[18:19], 0, v[214:215]
	global_load_lds_dwordx4 v[194:195], off
	s_mov_b32 m0, s31
	s_andn2_b64 vcc, exec, s[20:21]
	global_load_lds_dwordx4 v[226:227], off
	s_mov_b32 m0, s38
	s_nop 0
	global_load_lds_dwordx4 v[228:229], off
	s_waitcnt vmcnt(24)
	s_cbranch_vccnz .LBB0_235
	s_waitcnt vmcnt(8)
	s_branch .LBB0_235

; #define PG8_STAGE(bufoff, gbase, voff) do { _Pragma("unroll") for (int _i = 0; _i < 2; ++_i) \
;         __builtin_amdgcn_global_load_lds((const unsigned*)((const char*)(gbase) + (voff)[_i]), (PG8_LAS unsigned*)(lds + (bufoff) + ldsw + _i * 8192), 16, 0, 0); } while (0)
; #define PG8_LDA(dst, b, h) do { _Pragma("unroll") for (int m = 0; m < 4; ++m) _Pragma("unroll") for (int k = 0; k < 2; ++k) dst[m][k] = *(const PG8_LAS bf16x8*)(lds + PG8_SA(b, h) + aoff + m * 2048 + k * 1024); } while (0)
; #define PG8_MMA(ai, bj, At, Bt) do { __builtin_amdgcn_s_setprio(1); _Pragma("unroll") for (int m = 0; m < 4; ++m) _Pragma("unroll") for (int n = 0; n < 2; ++n) _Pragma("unroll") for (int k = 0; k < 2; ++k) \
;         acc[ai][bj][m][n] = __builtin_amdgcn_mfma_f32_16x16x32_bf16(Bt[n][k], At[m][k], acc[ai][bj][m][n], 0, 0, 0); __builtin_amdgcn_s_setprio(0); } while (0)
; #define PG8_WAIT_V(n) asm volatile("s_waitcnt vmcnt(" #n ")" ::: "memory")
; #define PG8_WAIT_VN(n) asm volatile("s_waitcnt vmcnt(%0)" :: "n"(n) : "memory")
; #define PG8_WAIT_L(n) asm volatile("s_waitcnt lgkmcnt(" #n ")" ::: "memory")
; #define PG8_BAR __builtin_amdgcn_s_barrier()
; #define PG8_SCHED __builtin_amdgcn_sched_barrier(0)
; template <class Epi, class Sched, bool ALIGN_EPI = false, bool SP2 = false>
; __device__ __forceinline__ void gemm_phase(PG8_LAS unsigned char* lds, const Gemm g, const Sched& S, const Epi& E, const int wave_id) {
;     ...
;             const char* a1 = cA + (size_t)(t + 1) * kstep;
;             const char* a2 = last ? nA : cA + (size_t)(t + 2) * kstep; const char* b2 = last ? nB : cB + (size_t)(t + 2) * kstep;
;     ...
;             PG8_WAIT_VN(8 + Epi::NS); if (strict) PG8_WAIT_V(8); PG8_WAIT_L(0); PG8_BAR; PG8_MMA(0, 0, At, B0); PG8_MMA(0, 1, At, B1); PG8_BAR; PG8_SCHED;
;             PG8_LDA(At, 0, 1); PG8_STAGE(PG8_SB(0, 0), b2, voffB); PG8_STAGE(PG8_SB(0, 1), b2 + hstep, voffB); PG8_STAGE(PG8_SA(0, 0), a2, voffA);
;             PG8_WAIT_VN(8 + Epi::NS); if (strict) PG8_WAIT_V(8); PG8_WAIT_L(0); PG8_BAR; PG8_MMA(1, 0, At, B0); PG8_MMA(1, 1, At, B1); PG8_BAR; PG8_SCHED;
.LBB0_307:
	s_add_u32 s12, s37, s10
	s_addc_u32 s13, s38, s11
	s_add_u32 s12, s12, 0x26300100
	s_addc_u32 s13, s13, 0
	s_add_u32 s40, s35, s10
	s_addc_u32 s41, s36, s11
	s_cmpk_eq_i32 s10, 0xa00
	s_cselect_b32 s15, s9, s13
	s_cselect_b32 s14, s8, s12
	s_cselect_b32 s13, s7, s41
	s_cselect_b32 s12, s6, s40
	s_waitcnt lgkmcnt(0)
	s_barrier
	s_setprio 1
	s_waitcnt lgkmcnt(0)
	v_mfma_f32_16x16x32_bf16 v[126:129], v[146:149], v[186:189], v[126:129]
	v_mfma_f32_16x16x32_bf16 v[122:125], v[154:157], v[186:189], v[122:125]
	v_mfma_f32_16x16x32_bf16 v[118:121], v[146:149], v[178:181], v[118:121]
	v_mfma_f32_16x16x32_bf16 v[114:117], v[154:157], v[178:181], v[114:117]
	v_mfma_f32_16x16x32_bf16 v[110:113], v[146:149], v[170:173], v[110:113]
	v_mfma_f32_16x16x32_bf16 v[102:105], v[154:157], v[170:173], v[102:105]
	v_mfma_f32_16x16x32_bf16 v[94:97], v[146:149], v[162:165], v[94:97]
	v_mfma_f32_16x16x32_bf16 v[86:89], v[154:157], v[162:165], v[86:89]
	v_mfma_f32_16x16x32_bf16 v[126:129], v[150:153], v[190:193], v[126:129]
	v_mfma_f32_16x16x32_bf16 v[122:125], v[158:161], v[190:193], v[122:125]
	v_mfma_f32_16x16x32_bf16 v[118:121], v[150:153], v[182:185], v[118:121]
	v_mfma_f32_16x16x32_bf16 v[114:117], v[158:161], v[182:185], v[114:117]
	v_mfma_f32_16x16x32_bf16 v[110:113], v[150:153], v[174:177], v[110:113]
	v_mfma_f32_16x16x32_bf16 v[102:105], v[158:161], v[174:177], v[102:105]
	v_mfma_f32_16x16x32_bf16 v[94:97], v[150:153], v[166:169], v[94:97]
	v_mfma_f32_16x16x32_bf16 v[86:89], v[158:161], v[166:169], v[86:89]
	s_setprio 0
	s_setprio 1
	v_mfma_f32_16x16x32_bf16 v[106:109], v[130:133], v[186:189], v[106:109]
	v_mfma_f32_16x16x32_bf16 v[98:101], v[138:141], v[186:189], v[98:101]
	v_mfma_f32_16x16x32_bf16 v[90:93], v[130:133], v[178:181], v[90:93]
	v_mfma_f32_16x16x32_bf16 v[82:85], v[138:141], v[178:181], v[82:85]
	v_mfma_f32_16x16x32_bf16 v[78:81], v[130:133], v[170:173], v[78:81]
	v_mfma_f32_16x16x32_bf16 v[74:77], v[138:141], v[170:173], v[74:77]
	v_mfma_f32_16x16x32_bf16 v[70:73], v[130:133], v[162:165], v[70:73]
	v_mfma_f32_16x16x32_bf16 v[66:69], v[138:141], v[162:165], v[66:69]
	v_mfma_f32_16x16x32_bf16 v[106:109], v[134:137], v[190:193], v[106:109]
	v_mfma_f32_16x16x32_bf16 v[98:101], v[142:145], v[190:193], v[98:101]
	v_mfma_f32_16x16x32_bf16 v[90:93], v[134:137], v[182:185], v[90:93]
	v_mfma_f32_16x16x32_bf16 v[82:85], v[142:145], v[182:185], v[82:85]
	v_mfma_f32_16x16x32_bf16 v[78:81], v[134:137], v[174:177], v[78:81]
	v_mfma_f32_16x16x32_bf16 v[74:77], v[142:145], v[174:177], v[74:77]
	v_mfma_f32_16x16x32_bf16 v[70:73], v[134:137], v[166:169], v[70:73]
	v_mfma_f32_16x16x32_bf16 v[66:69], v[142:145], v[166:169], v[66:69]
	s_setprio 0
	s_barrier
	s_mov_b32 m0, s23
	v_lshl_add_u64 v[228:229], s[12:13], 0, v[214:215]
	s_add_u32 s40, s12, 0xb0000
	ds_read_b128 v[186:189], v232 offset:16384
	ds_read_b128 v[190:193], v232 offset:17408
	ds_read_b128 v[178:181], v232 offset:18432
	ds_read_b128 v[182:185], v232 offset:19456
	ds_read_b128 v[170:173], v232 offset:20480
	ds_read_b128 v[174:177], v232 offset:21504
	ds_read_b128 v[162:165], v232 offset:22528
	ds_read_b128 v[166:169], v232 offset:23552
	global_load_lds_dwordx4 v[228:229], off
	v_lshl_add_u64 v[226:227], s[12:13], 0, v[210:211]
	s_mov_b32 m0, s24
	s_addc_u32 s41, s13, 0
	global_load_lds_dwordx4 v[226:227], off
	v_lshl_add_u64 v[194:195], s[40:41], 0, v[214:215]
	s_mov_b32 m0, s25
	v_lshl_add_u64 v[222:223], s[14:15], 0, v[216:217]
	global_load_lds_dwordx4 v[194:195], off
	v_lshl_add_u64 v[194:195], s[40:41], 0, v[210:211]
	s_mov_b32 m0, s26
	v_lshl_add_u64 v[224:225], s[14:15], 0, v[212:213]
	global_load_lds_dwordx4 v[194:195], off
	s_mov_b32 m0, s22
	s_andn2_b64 vcc, exec, s[16:17]
	global_load_lds_dwordx4 v[222:223], off
	s_mov_b32 m0, s28
	s_nop 0
	global_load_lds_dwordx4 v[224:225], off
	s_waitcnt vmcnt(24)
	s_cbranch_vccnz .LBB0_304
	s_waitcnt vmcnt(8)
	s_branch .LBB0_304

; #define PG8_STAGE(bufoff, gbase, voff) do { _Pragma("unroll") for (int _i = 0; _i < 2; ++_i) \
;         __builtin_amdgcn_global_load_lds((const unsigned*)((const char*)(gbase) + (voff)[_i]), (PG8_LAS unsigned*)(lds + (bufoff) + ldsw + _i * 8192), 16, 0, 0); } while (0)
; #define PG8_LDA(dst, b, h) do { _Pragma("unroll") for (int m = 0; m < 4; ++m) _Pragma("unroll") for (int k = 0; k < 2; ++k) dst[m][k] = *(const PG8_LAS bf16x8*)(lds + PG8_SA(b, h) + aoff + m * 2048 + k * 1024); } while (0)
; #define PG8_MMA(ai, bj, At, Bt) do { __builtin_amdgcn_s_setprio(1); _Pragma("unroll") for (int m = 0; m < 4; ++m) _Pragma("unroll") for (int n = 0; n < 2; ++n) _Pragma("unroll") for (int k = 0; k < 2; ++k) \
;         acc[ai][bj][m][n] = __builtin_amdgcn_mfma_f32_16x16x32_bf16(Bt[n][k], At[m][k], acc[ai][bj][m][n], 0, 0, 0); __builtin_amdgcn_s_setprio(0); } while (0)
; #define PG8_WAIT_V(n) asm volatile("s_waitcnt vmcnt(" #n ")" ::: "memory")
; #define PG8_WAIT_VN(n) asm volatile("s_waitcnt vmcnt(%0)" :: "n"(n) : "memory")
; #define PG8_WAIT_L(n) asm volatile("s_waitcnt lgkmcnt(" #n ")" ::: "memory")
; #define PG8_BAR __builtin_amdgcn_s_barrier()
; #define PG8_SCHED __builtin_amdgcn_sched_barrier(0)
; template <class Epi, class Sched, bool ALIGN_EPI = false, bool SP2 = false>
; __device__ __forceinline__ void gemm_phase(PG8_LAS unsigned char* lds, const Gemm g, const Sched& S, const Epi& E, const int wave_id) {
;     ...
;             const char* a1 = cA + (size_t)(t + 1) * kstep;
;             const char* a2 = last ? nA : cA + (size_t)(t + 2) * kstep; const char* b2 = last ? nB : cB + (size_t)(t + 2) * kstep;
;     ...
;             PG8_WAIT_VN(8 + Epi::NS); if (strict) PG8_WAIT_V(8); PG8_WAIT_L(0); PG8_BAR; PG8_MMA(0, 0, At, B0); PG8_MMA(0, 1, At, B1); PG8_BAR; PG8_SCHED;
;             PG8_LDA(At, 0, 1); PG8_STAGE(PG8_SB(0, 0), b2, voffB); PG8_STAGE(PG8_SB(0, 1), b2 + hstep, voffB); PG8_STAGE(PG8_SA(0, 0), a2, voffA);
;             PG8_WAIT_VN(8 + Epi::NS); if (strict) PG8_WAIT_V(8); PG8_WAIT_L(0); PG8_BAR; PG8_MMA(1, 0, At, B0); PG8_MMA(1, 1, At, B1); PG8_BAR; PG8_SCHED;
.LBB0_423:
	s_add_u32 s12, s8, s10
	s_addc_u32 s13, s9, s11
	s_add_u32 s12, s12, 0x100
	s_addc_u32 s13, s13, 0
	s_add_u32 s41, s36, s10
	s_addc_u32 s42, s37, s11
	s_cmpk_eq_i32 s10, 0x700
	s_cselect_b32 s15, s23, s13
	s_cselect_b32 s14, s29, s12
	s_cselect_b32 s13, s21, s42
	s_cselect_b32 s12, s31, s41
	s_waitcnt lgkmcnt(0)
	s_barrier
	s_setprio 1
	s_waitcnt lgkmcnt(0)
	v_mfma_f32_16x16x32_bf16 v[126:129], v[146:149], v[186:189], v[126:129]
	v_mfma_f32_16x16x32_bf16 v[122:125], v[154:157], v[186:189], v[122:125]
	v_mfma_f32_16x16x32_bf16 v[110:113], v[146:149], v[178:181], v[110:113]
	v_mfma_f32_16x16x32_bf16 v[106:109], v[154:157], v[178:181], v[106:109]
	v_mfma_f32_16x16x32_bf16 v[94:97], v[146:149], v[170:173], v[94:97]
	v_mfma_f32_16x16x32_bf16 v[90:93], v[154:157], v[170:173], v[90:93]
	v_mfma_f32_16x16x32_bf16 v[78:81], v[146:149], v[162:165], v[78:81]
	v_mfma_f32_16x16x32_bf16 v[74:77], v[154:157], v[162:165], v[74:77]
	v_mfma_f32_16x16x32_bf16 v[126:129], v[150:153], v[190:193], v[126:129]
	v_mfma_f32_16x16x32_bf16 v[122:125], v[158:161], v[190:193], v[122:125]
	v_mfma_f32_16x16x32_bf16 v[110:113], v[150:153], v[182:185], v[110:113]
	v_mfma_f32_16x16x32_bf16 v[106:109], v[158:161], v[182:185], v[106:109]
	v_mfma_f32_16x16x32_bf16 v[94:97], v[150:153], v[174:177], v[94:97]
	v_mfma_f32_16x16x32_bf16 v[90:93], v[158:161], v[174:177], v[90:93]
	v_mfma_f32_16x16x32_bf16 v[78:81], v[150:153], v[166:169], v[78:81]
	v_mfma_f32_16x16x32_bf16 v[74:77], v[158:161], v[166:169], v[74:77]
	s_setprio 0
	s_setprio 1
	v_mfma_f32_16x16x32_bf16 v[118:121], v[130:133], v[186:189], v[118:121]
	v_mfma_f32_16x16x32_bf16 v[114:117], v[138:141], v[186:189], v[114:117]
	v_mfma_f32_16x16x32_bf16 v[102:105], v[130:133], v[178:181], v[102:105]
	v_mfma_f32_16x16x32_bf16 v[98:101], v[138:141], v[178:181], v[98:101]
	v_mfma_f32_16x16x32_bf16 v[86:89], v[130:133], v[170:173], v[86:89]
	v_mfma_f32_16x16x32_bf16 v[82:85], v[138:141], v[170:173], v[82:85]
	v_mfma_f32_16x16x32_bf16 v[70:73], v[130:133], v[162:165], v[70:73]
	v_mfma_f32_16x16x32_bf16 v[66:69], v[138:141], v[162:165], v[66:69]
	v_mfma_f32_16x16x32_bf16 v[118:121], v[134:137], v[190:193], v[118:121]
	v_mfma_f32_16x16x32_bf16 v[114:117], v[142:145], v[190:193], v[114:117]
	v_mfma_f32_16x16x32_bf16 v[102:105], v[134:137], v[182:185], v[102:105]
	v_mfma_f32_16x16x32_bf16 v[98:101], v[142:145], v[182:185], v[98:101]
	v_mfma_f32_16x16x32_bf16 v[86:89], v[134:137], v[174:177], v[86:89]
	v_mfma_f32_16x16x32_bf16 v[82:85], v[142:145], v[174:177], v[82:85]
	v_mfma_f32_16x16x32_bf16 v[70:73], v[134:137], v[166:169], v[70:73]
	v_mfma_f32_16x16x32_bf16 v[66:69], v[142:145], v[166:169], v[66:69]
	s_setprio 0
	s_barrier
	s_mov_b32 m0, s94
	v_lshl_add_u64 v[232:233], s[12:13], 0, v[212:213]
	s_add_u32 s42, s12, 0x40000
	ds_read_b128 v[186:189], v247 offset:16384
	ds_read_b128 v[190:193], v247 offset:17408
	ds_read_b128 v[178:181], v247 offset:18432
	ds_read_b128 v[182:185], v247 offset:19456
	ds_read_b128 v[170:173], v247 offset:20480
	ds_read_b128 v[174:177], v247 offset:21504
	ds_read_b128 v[162:165], v247 offset:22528
	ds_read_b128 v[166:169], v247 offset:23552
	global_load_lds_dwordx4 v[232:233], off
	v_lshl_add_u64 v[230:231], s[12:13], 0, v[216:217]
	s_mov_b32 m0, s95
	s_addc_u32 s43, s13, 0
	global_load_lds_dwordx4 v[230:231], off
	v_lshl_add_u64 v[194:195], s[42:43], 0, v[212:213]
	s_mov_b32 m0, s38
	v_lshl_add_u64 v[226:227], s[14:15], 0, v[210:211]
	global_load_lds_dwordx4 v[194:195], off
	v_lshl_add_u64 v[194:195], s[42:43], 0, v[216:217]
	s_mov_b32 m0, s39
	v_lshl_add_u64 v[228:229], s[14:15], 0, v[214:215]
	global_load_lds_dwordx4 v[194:195], off
	s_mov_b32 m0, s91
	s_andn2_b64 vcc, exec, s[34:35]
	global_load_lds_dwordx4 v[226:227], off
	s_mov_b32 m0, s2
	s_nop 0
	global_load_lds_dwordx4 v[228:229], off
	s_waitcnt vmcnt(24)
	s_cbranch_vccnz .LBB0_420
	s_waitcnt vmcnt(8)
	s_branch .LBB0_420

; #define PG8_STAGE(bufoff, gbase, voff) do { _Pragma("unroll") for (int _i = 0; _i < 2; ++_i) \
;         __builtin_amdgcn_global_load_lds((const unsigned*)((const char*)(gbase) + (voff)[_i]), (PG8_LAS unsigned*)(lds + (bufoff) + ldsw + _i * 8192), 16, 0, 0); } while (0)
; #define PG8_LDA(dst, b, h) do { _Pragma("unroll") for (int m = 0; m < 4; ++m) _Pragma("unroll") for (int k = 0; k < 2; ++k) dst[m][k] = *(const PG8_LAS bf16x8*)(lds + PG8_SA(b, h) + aoff + m * 2048 + k * 1024); } while (0)
; #define PG8_MMA(ai, bj, At, Bt) do { __builtin_amdgcn_s_setprio(1); _Pragma("unroll") for (int m = 0; m < 4; ++m) _Pragma("unroll") for (int n = 0; n < 2; ++n) _Pragma("unroll") for (int k = 0; k < 2; ++k) \
;         acc[ai][bj][m][n] = __builtin_amdgcn_mfma_f32_16x16x32_bf16(Bt[n][k], At[m][k], acc[ai][bj][m][n], 0, 0, 0); __builtin_amdgcn_s_setprio(0); } while (0)
; #define PG8_WAIT_V(n) asm volatile("s_waitcnt vmcnt(" #n ")" ::: "memory")
; #define PG8_WAIT_VN(n) asm volatile("s_waitcnt vmcnt(%0)" :: "n"(n) : "memory")
; #define PG8_WAIT_L(n) asm volatile("s_waitcnt lgkmcnt(" #n ")" ::: "memory")
; #define PG8_BAR __builtin_amdgcn_s_barrier()
; #define PG8_SCHED __builtin_amdgcn_sched_barrier(0)
; template <class Epi, class Sched, bool ALIGN_EPI = false, bool SP2 = false>
; __device__ __forceinline__ void gemm_phase(PG8_LAS unsigned char* lds, const Gemm g, const Sched& S, const Epi& E, const int wave_id) {
;     ...
;             const char* a1 = cA + (size_t)(t + 1) * kstep;
;             const char* a2 = last ? nA : cA + (size_t)(t + 2) * kstep; const char* b2 = last ? nB : cB + (size_t)(t + 2) * kstep;
;     ...
;             PG8_WAIT_VN(8 + Epi::NS); if (strict) PG8_WAIT_V(8); PG8_WAIT_L(0); PG8_BAR; PG8_MMA(0, 0, At, B0); PG8_MMA(0, 1, At, B1); PG8_BAR; PG8_SCHED;
;             PG8_LDA(At, 0, 1); PG8_STAGE(PG8_SB(0, 0), b2, voffB); PG8_STAGE(PG8_SB(0, 1), b2 + hstep, voffB); PG8_STAGE(PG8_SA(0, 0), a2, voffA);
;             PG8_WAIT_VN(8 + Epi::NS); if (strict) PG8_WAIT_V(8); PG8_WAIT_L(0); PG8_BAR; PG8_MMA(1, 0, At, B0); PG8_MMA(1, 1, At, B1); PG8_BAR; PG8_SCHED;
.LBB0_1507:
	s_add_u32 s16, s41, s12
	s_addc_u32 s17, s42, s13
	s_add_u32 s16, s16, 0x8f2c0100
	s_addc_u32 s17, s17, 0
	s_add_u32 s49, s39, s12
	s_addc_u32 s50, s40, s13
	s_cmpk_eq_i32 s12, 0x700
	s_cselect_b32 s19, s11, s17
	s_cselect_b32 s18, s10, s16
	s_cselect_b32 s17, s9, s50
	s_cselect_b32 s16, s8, s49
	s_waitcnt lgkmcnt(0)
	s_barrier
	s_setprio 1
	s_waitcnt lgkmcnt(0)
	v_mfma_f32_16x16x32_bf16 v[126:129], v[146:149], v[186:189], v[126:129]
	v_mfma_f32_16x16x32_bf16 v[122:125], v[154:157], v[186:189], v[122:125]
	v_mfma_f32_16x16x32_bf16 v[110:113], v[146:149], v[178:181], v[110:113]
	v_mfma_f32_16x16x32_bf16 v[106:109], v[154:157], v[178:181], v[106:109]
	v_mfma_f32_16x16x32_bf16 v[94:97], v[146:149], v[170:173], v[94:97]
	v_mfma_f32_16x16x32_bf16 v[90:93], v[154:157], v[170:173], v[90:93]
	v_mfma_f32_16x16x32_bf16 v[78:81], v[146:149], v[162:165], v[78:81]
	v_mfma_f32_16x16x32_bf16 v[74:77], v[154:157], v[162:165], v[74:77]
	v_mfma_f32_16x16x32_bf16 v[126:129], v[150:153], v[190:193], v[126:129]
	v_mfma_f32_16x16x32_bf16 v[122:125], v[158:161], v[190:193], v[122:125]
	v_mfma_f32_16x16x32_bf16 v[110:113], v[150:153], v[182:185], v[110:113]
	v_mfma_f32_16x16x32_bf16 v[106:109], v[158:161], v[182:185], v[106:109]
	v_mfma_f32_16x16x32_bf16 v[94:97], v[150:153], v[174:177], v[94:97]
	v_mfma_f32_16x16x32_bf16 v[90:93], v[158:161], v[174:177], v[90:93]
	v_mfma_f32_16x16x32_bf16 v[78:81], v[150:153], v[166:169], v[78:81]
	v_mfma_f32_16x16x32_bf16 v[74:77], v[158:161], v[166:169], v[74:77]
	s_setprio 0
	s_setprio 1
	v_mfma_f32_16x16x32_bf16 v[118:121], v[130:133], v[186:189], v[118:121]
	v_mfma_f32_16x16x32_bf16 v[114:117], v[138:141], v[186:189], v[114:117]
	v_mfma_f32_16x16x32_bf16 v[102:105], v[130:133], v[178:181], v[102:105]
	v_mfma_f32_16x16x32_bf16 v[98:101], v[138:141], v[178:181], v[98:101]
	v_mfma_f32_16x16x32_bf16 v[86:89], v[130:133], v[170:173], v[86:89]
	v_mfma_f32_16x16x32_bf16 v[82:85], v[138:141], v[170:173], v[82:85]
	v_mfma_f32_16x16x32_bf16 v[70:73], v[130:133], v[162:165], v[70:73]
	v_mfma_f32_16x16x32_bf16 v[66:69], v[138:141], v[162:165], v[66:69]
	v_mfma_f32_16x16x32_bf16 v[118:121], v[134:137], v[190:193], v[118:121]
	v_mfma_f32_16x16x32_bf16 v[114:117], v[142:145], v[190:193], v[114:117]
	v_mfma_f32_16x16x32_bf16 v[102:105], v[134:137], v[182:185], v[102:105]
	v_mfma_f32_16x16x32_bf16 v[98:101], v[142:145], v[182:185], v[98:101]
	v_mfma_f32_16x16x32_bf16 v[86:89], v[134:137], v[174:177], v[86:89]
	v_mfma_f32_16x16x32_bf16 v[82:85], v[142:145], v[174:177], v[82:85]
	v_mfma_f32_16x16x32_bf16 v[70:73], v[134:137], v[166:169], v[70:73]
	v_mfma_f32_16x16x32_bf16 v[66:69], v[142:145], v[166:169], v[66:69]
	s_setprio 0
	s_barrier
	s_mov_b32 m0, s26
	v_lshl_add_u64 v[228:229], s[16:17], 0, v[214:215]
	s_add_u32 s50, s16, 0x40000
	ds_read_b128 v[186:189], v232 offset:16384
	ds_read_b128 v[190:193], v232 offset:17408
	ds_read_b128 v[178:181], v232 offset:18432
	ds_read_b128 v[182:185], v232 offset:19456
	ds_read_b128 v[170:173], v232 offset:20480
	ds_read_b128 v[174:177], v232 offset:21504
	ds_read_b128 v[162:165], v232 offset:22528
	ds_read_b128 v[166:169], v232 offset:23552
	global_load_lds_dwordx4 v[228:229], off
	v_lshl_add_u64 v[226:227], s[16:17], 0, v[210:211]
	s_mov_b32 m0, s27
	s_addc_u32 s51, s17, 0
	global_load_lds_dwordx4 v[226:227], off
	v_lshl_add_u64 v[194:195], s[50:51], 0, v[214:215]
	s_mov_b32 m0, s29
	v_lshl_add_u64 v[222:223], s[18:19], 0, v[216:217]
	global_load_lds_dwordx4 v[194:195], off
	v_lshl_add_u64 v[194:195], s[50:51], 0, v[210:211]
	s_mov_b32 m0, s30
	v_lshl_add_u64 v[224:225], s[18:19], 0, v[212:213]
	global_load_lds_dwordx4 v[194:195], off
	s_mov_b32 m0, s25
	s_andn2_b64 vcc, exec, s[20:21]
	global_load_lds_dwordx4 v[222:223], off
	s_mov_b32 m0, s34
	s_nop 0
	global_load_lds_dwordx4 v[224:225], off
	s_waitcnt vmcnt(24)
	s_cbranch_vccnz .LBB0_1504
	s_waitcnt vmcnt(8)
	s_branch .LBB0_1504

; #define PG8_STAGE(bufoff, gbase, voff) do { _Pragma("unroll") for (int _i = 0; _i < 2; ++_i) \
;         __builtin_amdgcn_global_load_lds((const unsigned*)((const char*)(gbase) + (voff)[_i]), (PG8_LAS unsigned*)(lds + (bufoff) + ldsw + _i * 8192), 16, 0, 0); } while (0)
; #define PG8_LDA(dst, b, h) do { _Pragma("unroll") for (int m = 0; m < 4; ++m) _Pragma("unroll") for (int k = 0; k < 2; ++k) dst[m][k] = *(const PG8_LAS bf16x8*)(lds + PG8_SA(b, h) + aoff + m * 2048 + k * 1024); } while (0)
; #define PG8_MMA(ai, bj, At, Bt) do { __builtin_amdgcn_s_setprio(1); _Pragma("unroll") for (int m = 0; m < 4; ++m) _Pragma("unroll") for (int n = 0; n < 2; ++n) _Pragma("unroll") for (int k = 0; k < 2; ++k) \
;         acc[ai][bj][m][n] = __builtin_amdgcn_mfma_f32_16x16x32_bf16(Bt[n][k], At[m][k], acc[ai][bj][m][n], 0, 0, 0); __builtin_amdgcn_s_setprio(0); } while (0)
; #define PG8_WAIT_V(n) asm volatile("s_waitcnt vmcnt(" #n ")" ::: "memory")
; #define PG8_WAIT_VN(n) asm volatile("s_waitcnt vmcnt(%0)" :: "n"(n) : "memory")
; #define PG8_WAIT_L(n) asm volatile("s_waitcnt lgkmcnt(" #n ")" ::: "memory")
; #define PG8_BAR __builtin_amdgcn_s_barrier()
; #define PG8_SCHED __builtin_amdgcn_sched_barrier(0)
; template <class Epi, class Sched, bool ALIGN_EPI = false, bool SP2 = false>
; __device__ __forceinline__ void gemm_phase(PG8_LAS unsigned char* lds, const Gemm g, const Sched& S, const Epi& E, const int wave_id) {
;     ...
;             const char* a1 = cA + (size_t)(t + 1) * kstep;
;             const char* a2 = last ? nA : cA + (size_t)(t + 2) * kstep; const char* b2 = last ? nB : cB + (size_t)(t + 2) * kstep;
;     ...
;             PG8_WAIT_VN(8 + Epi::NS); if (strict) PG8_WAIT_V(8); PG8_WAIT_L(0); PG8_BAR; PG8_MMA(0, 0, At, B0); PG8_MMA(0, 1, At, B1); PG8_BAR; PG8_SCHED;
;             PG8_LDA(At, 0, 1); PG8_STAGE(PG8_SB(0, 0), b2, voffB); PG8_STAGE(PG8_SB(0, 1), b2 + hstep, voffB); PG8_STAGE(PG8_SA(0, 0), a2, voffA);
;             PG8_WAIT_VN(8 + Epi::NS); if (strict) PG8_WAIT_V(8); PG8_WAIT_L(0); PG8_BAR; PG8_MMA(1, 0, At, B0); PG8_MMA(1, 1, At, B1); PG8_BAR; PG8_SCHED;
.LBB0_1824:
	s_add_u32 s22, s18, s20
	s_addc_u32 s23, s19, s21
	s_add_u32 s22, s22, 0x100
	s_addc_u32 s23, s23, 0
	s_add_u32 s53, s68, s20
	s_addc_u32 s75, s69, s21
	s_cmpk_eq_i32 s20, 0x700
	s_cselect_b32 s25, s11, s23
	s_cselect_b32 s24, s63, s22
	s_cselect_b32 s23, s9, s75
	s_cselect_b32 s22, s67, s53
	s_waitcnt lgkmcnt(0)
	s_barrier
	s_setprio 1
	s_waitcnt lgkmcnt(0)
	v_mfma_f32_16x16x32_bf16 v[126:129], v[146:149], v[186:189], v[126:129]
	v_mfma_f32_16x16x32_bf16 v[122:125], v[154:157], v[186:189], v[122:125]
	v_mfma_f32_16x16x32_bf16 v[110:113], v[146:149], v[178:181], v[110:113]
	v_mfma_f32_16x16x32_bf16 v[106:109], v[154:157], v[178:181], v[106:109]
	v_mfma_f32_16x16x32_bf16 v[94:97], v[146:149], v[170:173], v[94:97]
	v_mfma_f32_16x16x32_bf16 v[90:93], v[154:157], v[170:173], v[90:93]
	v_mfma_f32_16x16x32_bf16 v[78:81], v[146:149], v[162:165], v[78:81]
	v_mfma_f32_16x16x32_bf16 v[74:77], v[154:157], v[162:165], v[74:77]
	v_mfma_f32_16x16x32_bf16 v[126:129], v[150:153], v[190:193], v[126:129]
	v_mfma_f32_16x16x32_bf16 v[122:125], v[158:161], v[190:193], v[122:125]
	v_mfma_f32_16x16x32_bf16 v[110:113], v[150:153], v[182:185], v[110:113]
	v_mfma_f32_16x16x32_bf16 v[106:109], v[158:161], v[182:185], v[106:109]
	v_mfma_f32_16x16x32_bf16 v[94:97], v[150:153], v[174:177], v[94:97]
	v_mfma_f32_16x16x32_bf16 v[90:93], v[158:161], v[174:177], v[90:93]
	v_mfma_f32_16x16x32_bf16 v[78:81], v[150:153], v[166:169], v[78:81]
	v_mfma_f32_16x16x32_bf16 v[74:77], v[158:161], v[166:169], v[74:77]
	s_setprio 0
	s_setprio 1
	v_mfma_f32_16x16x32_bf16 v[118:121], v[130:133], v[186:189], v[118:121]
	v_mfma_f32_16x16x32_bf16 v[114:117], v[138:141], v[186:189], v[114:117]
	v_mfma_f32_16x16x32_bf16 v[102:105], v[130:133], v[178:181], v[102:105]
	v_mfma_f32_16x16x32_bf16 v[98:101], v[138:141], v[178:181], v[98:101]
	v_mfma_f32_16x16x32_bf16 v[86:89], v[130:133], v[170:173], v[86:89]
	v_mfma_f32_16x16x32_bf16 v[82:85], v[138:141], v[170:173], v[82:85]
	v_mfma_f32_16x16x32_bf16 v[70:73], v[130:133], v[162:165], v[70:73]
	v_mfma_f32_16x16x32_bf16 v[66:69], v[138:141], v[162:165], v[66:69]
	v_mfma_f32_16x16x32_bf16 v[118:121], v[134:137], v[190:193], v[118:121]
	v_mfma_f32_16x16x32_bf16 v[114:117], v[142:145], v[190:193], v[114:117]
	v_mfma_f32_16x16x32_bf16 v[102:105], v[134:137], v[182:185], v[102:105]
	v_mfma_f32_16x16x32_bf16 v[98:101], v[142:145], v[182:185], v[98:101]
	v_mfma_f32_16x16x32_bf16 v[86:89], v[134:137], v[174:177], v[86:89]
	v_mfma_f32_16x16x32_bf16 v[82:85], v[142:145], v[174:177], v[82:85]
	v_mfma_f32_16x16x32_bf16 v[70:73], v[134:137], v[166:169], v[70:73]
	v_mfma_f32_16x16x32_bf16 v[66:69], v[142:145], v[166:169], v[66:69]
	s_setprio 0
	s_barrier
	s_mov_b32 m0, s40
	v_lshl_add_u64 v[232:233], s[22:23], 0, v[212:213]
	s_add_u32 s90, s22, 0x40000
	ds_read_b128 v[186:189], v247 offset:16384
	ds_read_b128 v[190:193], v247 offset:17408
	ds_read_b128 v[178:181], v247 offset:18432
	ds_read_b128 v[182:185], v247 offset:19456
	ds_read_b128 v[170:173], v247 offset:20480
	ds_read_b128 v[174:177], v247 offset:21504
	ds_read_b128 v[162:165], v247 offset:22528
	ds_read_b128 v[166:169], v247 offset:23552
	global_load_lds_dwordx4 v[232:233], off
	v_lshl_add_u64 v[230:231], s[22:23], 0, v[216:217]
	s_mov_b32 m0, s41
	s_addc_u32 s91, s23, 0
	global_load_lds_dwordx4 v[230:231], off
	v_lshl_add_u64 v[194:195], s[90:91], 0, v[212:213]
	s_mov_b32 m0, s42
	v_lshl_add_u64 v[226:227], s[24:25], 0, v[210:211]
	global_load_lds_dwordx4 v[194:195], off
	v_lshl_add_u64 v[194:195], s[90:91], 0, v[216:217]
	s_mov_b32 m0, s43
	v_lshl_add_u64 v[228:229], s[24:25], 0, v[214:215]
	global_load_lds_dwordx4 v[194:195], off
	s_mov_b32 m0, s39
	s_andn2_b64 vcc, exec, s[26:27]
	global_load_lds_dwordx4 v[226:227], off
	s_mov_b32 m0, s49
	s_nop 0
	global_load_lds_dwordx4 v[228:229], off
	s_waitcnt vmcnt(24)
	s_cbranch_vccnz .LBB0_1821
	s_waitcnt vmcnt(8)
	s_branch .LBB0_1821

; #define PG8_STAGE(bufoff, gbase, voff) do { _Pragma("unroll") for (int _i = 0; _i < 2; ++_i) \
;         __builtin_amdgcn_global_load_lds((const unsigned*)((const char*)(gbase) + (voff)[_i]), (PG8_LAS unsigned*)(lds + (bufoff) + ldsw + _i * 8192), 16, 0, 0); } while (0)
; #define PG8_LDA(dst, b, h) do { _Pragma("unroll") for (int m = 0; m < 4; ++m) _Pragma("unroll") for (int k = 0; k < 2; ++k) dst[m][k] = *(const PG8_LAS bf16x8*)(lds + PG8_SA(b, h) + aoff + m * 2048 + k * 1024); } while (0)
; #define PG8_MMA(ai, bj, At, Bt) do { __builtin_amdgcn_s_setprio(1); _Pragma("unroll") for (int m = 0; m < 4; ++m) _Pragma("unroll") for (int n = 0; n < 2; ++n) _Pragma("unroll") for (int k = 0; k < 2; ++k) \
;         acc[ai][bj][m][n] = __builtin_amdgcn_mfma_f32_16x16x32_bf16(Bt[n][k], At[m][k], acc[ai][bj][m][n], 0, 0, 0); __builtin_amdgcn_s_setprio(0); } while (0)
; #define PG8_WAIT_V(n) asm volatile("s_waitcnt vmcnt(" #n ")" ::: "memory")
; #define PG8_WAIT_VN(n) asm volatile("s_waitcnt vmcnt(%0)" :: "n"(n) : "memory")
; #define PG8_WAIT_L(n) asm volatile("s_waitcnt lgkmcnt(" #n ")" ::: "memory")
; #define PG8_BAR __builtin_amdgcn_s_barrier()
; #define PG8_SCHED __builtin_amdgcn_sched_barrier(0)
; template <class Epi, class Sched, bool ALIGN_EPI = false, bool SP2 = false>
; __device__ __forceinline__ void gemm_phase(PG8_LAS unsigned char* lds, const Gemm g, const Sched& S, const Epi& E, const int wave_id) {
;     ...
;             const char* a1 = cA + (size_t)(t + 1) * kstep;
;             const char* a2 = last ? nA : cA + (size_t)(t + 2) * kstep; const char* b2 = last ? nB : cB + (size_t)(t + 2) * kstep;
;     ...
;             PG8_WAIT_VN(8 + Epi::NS); if (strict) PG8_WAIT_V(8); PG8_WAIT_L(0); PG8_BAR; PG8_MMA(0, 0, At, B0); PG8_MMA(0, 1, At, B1); PG8_BAR; PG8_SCHED;
;             PG8_LDA(At, 0, 1); PG8_STAGE(PG8_SB(0, 0), b2, voffB); PG8_STAGE(PG8_SB(0, 1), b2 + hstep, voffB); PG8_STAGE(PG8_SA(0, 0), a2, voffA);
;             PG8_WAIT_VN(8 + Epi::NS); if (strict) PG8_WAIT_V(8); PG8_WAIT_L(0); PG8_BAR; PG8_MMA(1, 0, At, B0); PG8_MMA(1, 1, At, B1); PG8_BAR; PG8_SCHED;
.LBB0_1892:
	s_add_u32 s12, s36, s10
	s_addc_u32 s13, s37, s11
	s_add_u32 s12, s12, 0x8200100
	s_addc_u32 s13, s13, 0
	s_add_u32 s39, s34, s10
	s_addc_u32 s40, s35, s11
	s_cmpk_eq_i32 s10, 0x700
	s_cselect_b32 s15, s9, s13
	s_cselect_b32 s14, s8, s12
	s_cselect_b32 s13, s7, s40
	s_cselect_b32 s12, s6, s39
	s_waitcnt lgkmcnt(0)
	s_barrier
	s_setprio 1
	s_waitcnt lgkmcnt(0)
	v_mfma_f32_16x16x32_bf16 v[126:129], v[146:149], v[186:189], v[126:129]
	v_mfma_f32_16x16x32_bf16 v[122:125], v[154:157], v[186:189], v[122:125]
	v_mfma_f32_16x16x32_bf16 v[118:121], v[146:149], v[178:181], v[118:121]
	v_mfma_f32_16x16x32_bf16 v[114:117], v[154:157], v[178:181], v[114:117]
	v_mfma_f32_16x16x32_bf16 v[94:97], v[146:149], v[170:173], v[94:97]
	v_mfma_f32_16x16x32_bf16 v[90:93], v[154:157], v[170:173], v[90:93]
	v_mfma_f32_16x16x32_bf16 v[86:89], v[146:149], v[162:165], v[86:89]
	v_mfma_f32_16x16x32_bf16 v[82:85], v[154:157], v[162:165], v[82:85]
	v_mfma_f32_16x16x32_bf16 v[126:129], v[150:153], v[190:193], v[126:129]
	v_mfma_f32_16x16x32_bf16 v[122:125], v[158:161], v[190:193], v[122:125]
	v_mfma_f32_16x16x32_bf16 v[118:121], v[150:153], v[182:185], v[118:121]
	v_mfma_f32_16x16x32_bf16 v[114:117], v[158:161], v[182:185], v[114:117]
	v_mfma_f32_16x16x32_bf16 v[94:97], v[150:153], v[174:177], v[94:97]
	v_mfma_f32_16x16x32_bf16 v[90:93], v[158:161], v[174:177], v[90:93]
	v_mfma_f32_16x16x32_bf16 v[86:89], v[150:153], v[166:169], v[86:89]
	v_mfma_f32_16x16x32_bf16 v[82:85], v[158:161], v[166:169], v[82:85]
	s_setprio 0
	s_setprio 1
	v_mfma_f32_16x16x32_bf16 v[110:113], v[130:133], v[186:189], v[110:113]
	v_mfma_f32_16x16x32_bf16 v[106:109], v[138:141], v[186:189], v[106:109]
	v_mfma_f32_16x16x32_bf16 v[102:105], v[130:133], v[178:181], v[102:105]
	v_mfma_f32_16x16x32_bf16 v[98:101], v[138:141], v[178:181], v[98:101]
	v_mfma_f32_16x16x32_bf16 v[78:81], v[130:133], v[170:173], v[78:81]
	v_mfma_f32_16x16x32_bf16 v[74:77], v[138:141], v[170:173], v[74:77]
	v_mfma_f32_16x16x32_bf16 v[70:73], v[130:133], v[162:165], v[70:73]
	v_mfma_f32_16x16x32_bf16 v[66:69], v[138:141], v[162:165], v[66:69]
	v_mfma_f32_16x16x32_bf16 v[110:113], v[134:137], v[190:193], v[110:113]
	v_mfma_f32_16x16x32_bf16 v[106:109], v[142:145], v[190:193], v[106:109]
	v_mfma_f32_16x16x32_bf16 v[102:105], v[134:137], v[182:185], v[102:105]
	v_mfma_f32_16x16x32_bf16 v[98:101], v[142:145], v[182:185], v[98:101]
	v_mfma_f32_16x16x32_bf16 v[78:81], v[134:137], v[174:177], v[78:81]
	v_mfma_f32_16x16x32_bf16 v[74:77], v[142:145], v[174:177], v[74:77]
	v_mfma_f32_16x16x32_bf16 v[70:73], v[134:137], v[166:169], v[70:73]
	v_mfma_f32_16x16x32_bf16 v[66:69], v[142:145], v[166:169], v[66:69]
	s_setprio 0
	s_barrier
	s_mov_b32 m0, s22
	v_lshl_add_u64 v[228:229], s[12:13], 0, v[212:213]
	s_add_u32 s40, s12, 0x40000
	ds_read_b128 v[186:189], v232 offset:16384
	ds_read_b128 v[190:193], v232 offset:17408
	ds_read_b128 v[178:181], v232 offset:18432
	ds_read_b128 v[182:185], v232 offset:19456
	ds_read_b128 v[170:173], v232 offset:20480
	ds_read_b128 v[174:177], v232 offset:21504
	ds_read_b128 v[162:165], v232 offset:22528
	ds_read_b128 v[166:169], v232 offset:23552
	global_load_lds_dwordx4 v[228:229], off
	v_lshl_add_u64 v[226:227], s[12:13], 0, v[216:217]
	s_mov_b32 m0, s23
	s_addc_u32 s41, s13, 0
	global_load_lds_dwordx4 v[226:227], off
	v_lshl_add_u64 v[194:195], s[40:41], 0, v[212:213]
	s_mov_b32 m0, s24
	v_lshl_add_u64 v[222:223], s[14:15], 0, v[210:211]
	global_load_lds_dwordx4 v[194:195], off
	v_lshl_add_u64 v[194:195], s[40:41], 0, v[216:217]
	s_mov_b32 m0, s25
	v_lshl_add_u64 v[224:225], s[14:15], 0, v[214:215]
	global_load_lds_dwordx4 v[194:195], off
	s_mov_b32 m0, s5
	s_andn2_b64 vcc, exec, s[16:17]
	global_load_lds_dwordx4 v[222:223], off
	s_mov_b32 m0, s26
	s_nop 0
	global_load_lds_dwordx4 v[224:225], off
	s_waitcnt vmcnt(16)
	s_cbranch_vccnz .LBB0_1889
	s_waitcnt vmcnt(8)
	s_branch .LBB0_1889

; #define PG8_STAGE(bufoff, gbase, voff) do { _Pragma("unroll") for (int _i = 0; _i < 2; ++_i) \
;         __builtin_amdgcn_global_load_lds((const unsigned*)((const char*)(gbase) + (voff)[_i]), (PG8_LAS unsigned*)(lds + (bufoff) + ldsw + _i * 8192), 16, 0, 0); } while (0)
; #define PG8_LDA(dst, b, h) do { _Pragma("unroll") for (int m = 0; m < 4; ++m) _Pragma("unroll") for (int k = 0; k < 2; ++k) dst[m][k] = *(const PG8_LAS bf16x8*)(lds + PG8_SA(b, h) + aoff + m * 2048 + k * 1024); } while (0)
; #define PG8_MMA(ai, bj, At, Bt) do { __builtin_amdgcn_s_setprio(1); _Pragma("unroll") for (int m = 0; m < 4; ++m) _Pragma("unroll") for (int n = 0; n < 2; ++n) _Pragma("unroll") for (int k = 0; k < 2; ++k) \
;         acc[ai][bj][m][n] = __builtin_amdgcn_mfma_f32_16x16x32_bf16(Bt[n][k], At[m][k], acc[ai][bj][m][n], 0, 0, 0); __builtin_amdgcn_s_setprio(0); } while (0)
; #define PG8_WAIT_V(n) asm volatile("s_waitcnt vmcnt(" #n ")" ::: "memory")
; #define PG8_WAIT_VN(n) asm volatile("s_waitcnt vmcnt(%0)" :: "n"(n) : "memory")
; #define PG8_WAIT_L(n) asm volatile("s_waitcnt lgkmcnt(" #n ")" ::: "memory")
; #define PG8_BAR __builtin_amdgcn_s_barrier()
; #define PG8_SCHED __builtin_amdgcn_sched_barrier(0)
; template <class Epi, class Sched, bool ALIGN_EPI = false, bool SP2 = false>
; __device__ __forceinline__ void gemm_phase(PG8_LAS unsigned char* lds, const Gemm g, const Sched& S, const Epi& E, const int wave_id) {
;     ...
;             const char* a1 = cA + (size_t)(t + 1) * kstep;
;             const char* a2 = last ? nA : cA + (size_t)(t + 2) * kstep; const char* b2 = last ? nB : cB + (size_t)(t + 2) * kstep;
;     ...
;             PG8_WAIT_VN(8 + Epi::NS); if (strict) PG8_WAIT_V(8); PG8_WAIT_L(0); PG8_BAR; PG8_MMA(0, 0, At, B0); PG8_MMA(0, 1, At, B1); PG8_BAR; PG8_SCHED;
;             PG8_LDA(At, 0, 1); PG8_STAGE(PG8_SB(0, 0), b2, voffB); PG8_STAGE(PG8_SB(0, 1), b2 + hstep, voffB); PG8_STAGE(PG8_SA(0, 0), a2, voffA);
;             PG8_WAIT_VN(8 + Epi::NS); if (strict) PG8_WAIT_V(8); PG8_WAIT_L(0); PG8_BAR; PG8_MMA(1, 0, At, B0); PG8_MMA(1, 1, At, B1); PG8_BAR; PG8_SCHED;
.LBB0_1955:
	s_add_u32 s24, s20, s22
	s_addc_u32 s25, s21, s23
	s_add_u32 s24, s24, 0x100
	s_addc_u32 s25, s25, 0
	s_add_u32 s53, s74, s22
	s_addc_u32 s78, s75, s23
	s_cmpk_eq_i32 s22, 0x700
	s_cselect_b32 s27, s13, s25
	s_cselect_b32 s26, s68, s24
	s_cselect_b32 s25, s11, s78
	s_cselect_b32 s24, s69, s53
	s_waitcnt lgkmcnt(0)
	s_barrier
	s_setprio 1
	s_waitcnt lgkmcnt(0)
	v_mfma_f32_16x16x32_bf16 v[126:129], v[146:149], v[186:189], v[126:129]
	v_mfma_f32_16x16x32_bf16 v[122:125], v[154:157], v[186:189], v[122:125]
	v_mfma_f32_16x16x32_bf16 v[118:121], v[146:149], v[178:181], v[118:121]
	v_mfma_f32_16x16x32_bf16 v[114:117], v[154:157], v[178:181], v[114:117]
	v_mfma_f32_16x16x32_bf16 v[94:97], v[146:149], v[170:173], v[94:97]
	v_mfma_f32_16x16x32_bf16 v[90:93], v[154:157], v[170:173], v[90:93]
	v_mfma_f32_16x16x32_bf16 v[86:89], v[146:149], v[162:165], v[86:89]
	v_mfma_f32_16x16x32_bf16 v[82:85], v[154:157], v[162:165], v[82:85]
	v_mfma_f32_16x16x32_bf16 v[126:129], v[150:153], v[190:193], v[126:129]
	v_mfma_f32_16x16x32_bf16 v[122:125], v[158:161], v[190:193], v[122:125]
	v_mfma_f32_16x16x32_bf16 v[118:121], v[150:153], v[182:185], v[118:121]
	v_mfma_f32_16x16x32_bf16 v[114:117], v[158:161], v[182:185], v[114:117]
	v_mfma_f32_16x16x32_bf16 v[94:97], v[150:153], v[174:177], v[94:97]
	v_mfma_f32_16x16x32_bf16 v[90:93], v[158:161], v[174:177], v[90:93]
	v_mfma_f32_16x16x32_bf16 v[86:89], v[150:153], v[166:169], v[86:89]
	v_mfma_f32_16x16x32_bf16 v[82:85], v[158:161], v[166:169], v[82:85]
	s_setprio 0
	s_setprio 1
	v_mfma_f32_16x16x32_bf16 v[110:113], v[130:133], v[186:189], v[110:113]
	v_mfma_f32_16x16x32_bf16 v[106:109], v[138:141], v[186:189], v[106:109]
	v_mfma_f32_16x16x32_bf16 v[102:105], v[130:133], v[178:181], v[102:105]
	v_mfma_f32_16x16x32_bf16 v[98:101], v[138:141], v[178:181], v[98:101]
	v_mfma_f32_16x16x32_bf16 v[78:81], v[130:133], v[170:173], v[78:81]
	v_mfma_f32_16x16x32_bf16 v[74:77], v[138:141], v[170:173], v[74:77]
	v_mfma_f32_16x16x32_bf16 v[70:73], v[130:133], v[162:165], v[70:73]
	v_mfma_f32_16x16x32_bf16 v[66:69], v[138:141], v[162:165], v[66:69]
	v_mfma_f32_16x16x32_bf16 v[110:113], v[134:137], v[190:193], v[110:113]
	v_mfma_f32_16x16x32_bf16 v[106:109], v[142:145], v[190:193], v[106:109]
	v_mfma_f32_16x16x32_bf16 v[102:105], v[134:137], v[182:185], v[102:105]
	v_mfma_f32_16x16x32_bf16 v[98:101], v[142:145], v[182:185], v[98:101]
	v_mfma_f32_16x16x32_bf16 v[78:81], v[134:137], v[174:177], v[78:81]
	v_mfma_f32_16x16x32_bf16 v[74:77], v[142:145], v[174:177], v[74:77]
	v_mfma_f32_16x16x32_bf16 v[70:73], v[134:137], v[166:169], v[70:73]
	v_mfma_f32_16x16x32_bf16 v[66:69], v[142:145], v[166:169], v[66:69]
	s_setprio 0
	s_barrier
	s_mov_b32 m0, s42
	v_lshl_add_u64 v[232:233], s[24:25], 0, v[214:215]
	s_add_u32 s90, s24, 0x40000
	ds_read_b128 v[186:189], v247 offset:16384
	ds_read_b128 v[190:193], v247 offset:17408
	ds_read_b128 v[178:181], v247 offset:18432
	ds_read_b128 v[182:185], v247 offset:19456
	ds_read_b128 v[170:173], v247 offset:20480
	ds_read_b128 v[174:177], v247 offset:21504
	ds_read_b128 v[162:165], v247 offset:22528
	ds_read_b128 v[166:169], v247 offset:23552
	global_load_lds_dwordx4 v[232:233], off
	v_lshl_add_u64 v[230:231], s[24:25], 0, v[210:211]
	s_mov_b32 m0, s43
	s_addc_u32 s91, s25, 0
	global_load_lds_dwordx4 v[230:231], off
	v_lshl_add_u64 v[194:195], s[90:91], 0, v[214:215]
	s_mov_b32 m0, s49
	v_lshl_add_u64 v[226:227], s[26:27], 0, v[216:217]
	global_load_lds_dwordx4 v[194:195], off
	v_lshl_add_u64 v[194:195], s[90:91], 0, v[210:211]
	s_mov_b32 m0, s50
	v_lshl_add_u64 v[228:229], s[26:27], 0, v[212:213]
	global_load_lds_dwordx4 v[194:195], off
	s_mov_b32 m0, s41
	s_andn2_b64 vcc, exec, s[28:29]
	global_load_lds_dwordx4 v[226:227], off
	s_mov_b32 m0, s51
	s_nop 0
	global_load_lds_dwordx4 v[228:229], off
	s_waitcnt vmcnt(16)
	s_cbranch_vccnz .LBB0_1952
	s_waitcnt vmcnt(8)
	s_branch .LBB0_1952

; #define PG8_STAGE(bufoff, gbase, voff) do { _Pragma("unroll") for (int _i = 0; _i < 2; ++_i) \
;         __builtin_amdgcn_global_load_lds((const unsigned*)((const char*)(gbase) + (voff)[_i]), (PG8_LAS unsigned*)(lds + (bufoff) + ldsw + _i * 8192), 16, 0, 0); } while (0)
; #define PG8_LDA(dst, b, h) do { _Pragma("unroll") for (int m = 0; m < 4; ++m) _Pragma("unroll") for (int k = 0; k < 2; ++k) dst[m][k] = *(const PG8_LAS bf16x8*)(lds + PG8_SA(b, h) + aoff + m * 2048 + k * 1024); } while (0)
; #define PG8_MMA(ai, bj, At, Bt) do { __builtin_amdgcn_s_setprio(1); _Pragma("unroll") for (int m = 0; m < 4; ++m) _Pragma("unroll") for (int n = 0; n < 2; ++n) _Pragma("unroll") for (int k = 0; k < 2; ++k) \
;         acc[ai][bj][m][n] = __builtin_amdgcn_mfma_f32_16x16x32_bf16(Bt[n][k], At[m][k], acc[ai][bj][m][n], 0, 0, 0); __builtin_amdgcn_s_setprio(0); } while (0)
; #define PG8_WAIT_V(n) asm volatile("s_waitcnt vmcnt(" #n ")" ::: "memory")
; #define PG8_WAIT_VN(n) asm volatile("s_waitcnt vmcnt(%0)" :: "n"(n) : "memory")
; #define PG8_WAIT_L(n) asm volatile("s_waitcnt lgkmcnt(" #n ")" ::: "memory")
; #define PG8_BAR __builtin_amdgcn_s_barrier()
; #define PG8_SCHED __builtin_amdgcn_sched_barrier(0)
; template <class Epi, class Sched, bool ALIGN_EPI = false, bool SP2 = false>
; __device__ __forceinline__ void gemm_phase(PG8_LAS unsigned char* lds, const Gemm g, const Sched& S, const Epi& E, const int wave_id) {
;     ...
;             const char* a1 = cA + (size_t)(t + 1) * kstep;
;             const char* a2 = last ? nA : cA + (size_t)(t + 2) * kstep; const char* b2 = last ? nB : cB + (size_t)(t + 2) * kstep;
;     ...
;             PG8_WAIT_VN(8 + Epi::NS); if (strict) PG8_WAIT_V(8); PG8_WAIT_L(0); PG8_BAR; PG8_MMA(0, 0, At, B0); PG8_MMA(0, 1, At, B1); PG8_BAR; PG8_SCHED;
;             PG8_LDA(At, 0, 1); PG8_STAGE(PG8_SB(0, 0), b2, voffB); PG8_STAGE(PG8_SB(0, 1), b2 + hstep, voffB); PG8_STAGE(PG8_SA(0, 0), a2, voffA);
;             PG8_WAIT_VN(8 + Epi::NS); if (strict) PG8_WAIT_V(8); PG8_WAIT_L(0); PG8_BAR; PG8_MMA(1, 0, At, B0); PG8_MMA(1, 1, At, B1); PG8_BAR; PG8_SCHED;
.LBB0_2033:
	s_add_u32 s16, s12, s14
	s_addc_u32 s17, s13, s15
	s_add_u32 s16, s16, 0x100
	s_addc_u32 s17, s17, 0
	s_add_u32 s53, s57, s14
	s_addc_u32 s67, s62, s15
	s_cmpk_eq_i32 s14, 0x1500
	s_cselect_b32 s19, s9, s17
	s_cselect_b32 s18, s8, s16
	s_cselect_b32 s17, s11, s67
	s_cselect_b32 s16, s10, s53
	s_waitcnt lgkmcnt(0)
	s_barrier
	s_setprio 1
	s_waitcnt lgkmcnt(0)
	v_mfma_f32_16x16x32_bf16 v[126:129], v[146:149], v[186:189], v[126:129]
	v_mfma_f32_16x16x32_bf16 v[122:125], v[154:157], v[186:189], v[122:125]
	v_mfma_f32_16x16x32_bf16 v[110:113], v[146:149], v[178:181], v[110:113]
	v_mfma_f32_16x16x32_bf16 v[106:109], v[154:157], v[178:181], v[106:109]
	v_mfma_f32_16x16x32_bf16 v[94:97], v[146:149], v[170:173], v[94:97]
	v_mfma_f32_16x16x32_bf16 v[90:93], v[154:157], v[170:173], v[90:93]
	v_mfma_f32_16x16x32_bf16 v[78:81], v[146:149], v[162:165], v[78:81]
	v_mfma_f32_16x16x32_bf16 v[74:77], v[154:157], v[162:165], v[74:77]
	v_mfma_f32_16x16x32_bf16 v[126:129], v[150:153], v[190:193], v[126:129]
	v_mfma_f32_16x16x32_bf16 v[122:125], v[158:161], v[190:193], v[122:125]
	v_mfma_f32_16x16x32_bf16 v[110:113], v[150:153], v[182:185], v[110:113]
	v_mfma_f32_16x16x32_bf16 v[106:109], v[158:161], v[182:185], v[106:109]
	v_mfma_f32_16x16x32_bf16 v[94:97], v[150:153], v[174:177], v[94:97]
	v_mfma_f32_16x16x32_bf16 v[90:93], v[158:161], v[174:177], v[90:93]
	v_mfma_f32_16x16x32_bf16 v[78:81], v[150:153], v[166:169], v[78:81]
	v_mfma_f32_16x16x32_bf16 v[74:77], v[158:161], v[166:169], v[74:77]
	s_setprio 0
	s_setprio 1
	v_mfma_f32_16x16x32_bf16 v[118:121], v[130:133], v[186:189], v[118:121]
	v_mfma_f32_16x16x32_bf16 v[114:117], v[138:141], v[186:189], v[114:117]
	v_mfma_f32_16x16x32_bf16 v[102:105], v[130:133], v[178:181], v[102:105]
	v_mfma_f32_16x16x32_bf16 v[98:101], v[138:141], v[178:181], v[98:101]
	v_mfma_f32_16x16x32_bf16 v[86:89], v[130:133], v[170:173], v[86:89]
	v_mfma_f32_16x16x32_bf16 v[82:85], v[138:141], v[170:173], v[82:85]
	v_mfma_f32_16x16x32_bf16 v[70:73], v[130:133], v[162:165], v[70:73]
	v_mfma_f32_16x16x32_bf16 v[66:69], v[138:141], v[162:165], v[66:69]
	v_mfma_f32_16x16x32_bf16 v[118:121], v[134:137], v[190:193], v[118:121]
	v_mfma_f32_16x16x32_bf16 v[114:117], v[142:145], v[190:193], v[114:117]
	v_mfma_f32_16x16x32_bf16 v[102:105], v[134:137], v[182:185], v[102:105]
	v_mfma_f32_16x16x32_bf16 v[98:101], v[142:145], v[182:185], v[98:101]
	v_mfma_f32_16x16x32_bf16 v[86:89], v[134:137], v[174:177], v[86:89]
	v_mfma_f32_16x16x32_bf16 v[82:85], v[142:145], v[174:177], v[82:85]
	v_mfma_f32_16x16x32_bf16 v[70:73], v[134:137], v[166:169], v[70:73]
	v_mfma_f32_16x16x32_bf16 v[66:69], v[142:145], v[166:169], v[66:69]
	s_setprio 0
	s_barrier
	s_mov_b32 m0, s34
	v_lshl_add_u64 v[232:233], s[16:17], 0, v[212:213]
	s_add_u32 s68, s16, 0xb0000
	ds_read_b128 v[186:189], v247 offset:16384
	ds_read_b128 v[190:193], v247 offset:17408
	ds_read_b128 v[178:181], v247 offset:18432
	ds_read_b128 v[182:185], v247 offset:19456
	ds_read_b128 v[170:173], v247 offset:20480
	ds_read_b128 v[174:177], v247 offset:21504
	ds_read_b128 v[162:165], v247 offset:22528
	ds_read_b128 v[166:169], v247 offset:23552
	global_load_lds_dwordx4 v[232:233], off
	v_lshl_add_u64 v[230:231], s[16:17], 0, v[216:217]
	s_mov_b32 m0, s35
	s_addc_u32 s69, s17, 0
	global_load_lds_dwordx4 v[230:231], off
	v_lshl_add_u64 v[194:195], s[68:69], 0, v[212:213]
	s_mov_b32 m0, s36
	v_lshl_add_u64 v[226:227], s[18:19], 0, v[210:211]
	global_load_lds_dwordx4 v[194:195], off
	v_lshl_add_u64 v[194:195], s[68:69], 0, v[216:217]
	s_mov_b32 m0, s37
	v_lshl_add_u64 v[228:229], s[18:19], 0, v[214:215]
	global_load_lds_dwordx4 v[194:195], off
	s_mov_b32 m0, s31
	s_andn2_b64 vcc, exec, s[20:21]
	global_load_lds_dwordx4 v[226:227], off
	s_mov_b32 m0, s38
	s_nop 0
	global_load_lds_dwordx4 v[228:229], off
	s_waitcnt vmcnt(24)
	s_cbranch_vccnz .LBB0_2030
	s_waitcnt vmcnt(8)
	s_branch .LBB0_2030
